# LDS-DMA attention staging: first-tile DMA issued before waiting for the Q fragment loads (latencies overlap) and the now-unneeded prologue barrier removed
# baseline (speedup 1.0000x reference)
.LBB0_747:
	s_and_b64 vcc, exec, s[10:11]
	s_cbranch_vccz .LBB0_751
	v_mov_b32_e32 v10, v232
	v_and_b32_e32 v181, 63, v10
	s_load_dwordx2 s[42:43], s[44:45], 0xb0
	s_waitcnt lgkmcnt(0)
	s_add_i32 s6, s37, s48
	s_lshl_b32 s14, s36, 7
	s_lshl_b32 s30, s36, 8
	v_readlane_b32 s11, v255, 21
	s_add_u32 s10, s42, s47
	s_addc_u32 s11, s43, s46
	s_add_u32 s36, s10, s30
	s_addc_u32 s37, s11, 0
	s_lshl_b32 s10, s27, 10
	s_or_b32 s10, s14, s10
	s_mul_hi_i32 s11, s10, 0x2200
	s_mulk_i32 s10, 0x2200
	v_ashrrev_i32_e32 v50, 4, v10
	s_add_u32 s10, s42, s10
	v_ashrrev_i32_e32 v51, 31, v50
	v_and_b32_e32 v177, 15, v10
	s_addc_u32 s11, s43, s11
	v_lshlrev_b64 v[52:53], 11, v[50:51]
	s_add_u32 s40, s10, 0xe010000
	v_lshl_add_u64 v[2:3], s[36:37], 0, v[52:53]
	v_lshlrev_b32_e32 v124, 4, v177
	v_mov_b32_e32 v125, v0
	s_addc_u32 s41, s11, 0
	v_lshl_add_u64 v[2:3], v[2:3], 0, v[124:125]
	s_mov_b32 s15, 0x16810000
	v_mov_b64_e32 v[4:5], s[40:41]
	s_movk_i32 s35, 0x2200
	v_add_co_u32_e32 v6, vcc, s15, v2
	v_mad_i64_i32 v[4:5], s[36:37], v50, s35, v[4:5]
	s_nop 0
	v_addc_co_u32_e32 v7, vcc, 0, v3, vcc
	s_mov_b32 s15, 0x16820000
	v_lshl_add_u64 v[4:5], v[4:5], 0, v[124:125]
	v_add_co_u32_e32 v6, vcc, s15, v2
	s_mov_b32 s15, 0x44000
	s_nop 0
	v_addc_co_u32_e32 v7, vcc, 0, v3, vcc
	v_add_co_u32_e32 v8, vcc, s15, v4
	s_mov_b32 s15, 0x16830000
	s_nop 0
	v_addc_co_u32_e32 v9, vcc, 0, v5, vcc
	v_add_co_u32_e32 v6, vcc, s15, v2
	s_mov_b32 s15, 0x88000
	s_nop 0
	v_addc_co_u32_e32 v7, vcc, 0, v3, vcc
	v_add_co_u32_e32 v8, vcc, s15, v4
	s_mov_b32 s15, 0x16840000
	s_nop 0
	v_addc_co_u32_e32 v9, vcc, 0, v5, vcc
	v_add_co_u32_e32 v2, vcc, s15, v2
	s_mov_b32 s15, 0xcc000
	s_nop 0
	v_addc_co_u32_e32 v3, vcc, 0, v3, vcc
	v_add_co_u32_e32 v4, vcc, s15, v4
	v_addc_co_u32_e32 v5, vcc, 0, v5, vcc
	v_ashrrev_i32_e32 v4, 2, v10
	v_and_b32_e32 v4, 0xffffffe0, v4
	v_add_u32_e32 v180, s6, v4
	v_ashrrev_i32_e32 v182, 6, v10
	v_and_b32_e32 v179, 1, v182
	v_mov_b32_e32 v55, v0
	v_lshlrev_b32_e32 v54, 7, v179
	v_and_b32_e32 v56, 48, v10
	v_mov_b32_e32 v57, v0
	s_mov_b32 s6, 0x14610000
	s_mov_b64 s[36:37], 0x14610000
	v_and_b32_e32 v2, 31, v223
	v_or_b32_e32 v2, v180, v2
	v_bfe_u32 v178, v10, 4, 2
	v_lshlrev_b32_e32 v51, 1, v50
	v_ashrrev_i32_e32 v3, 31, v2
	v_lshlrev_b64 v[2:3], 11, v[2:3]
	v_lshl_add_u64 v[2:3], s[42:43], 0, v[2:3]
	v_lshl_add_u64 v[2:3], v[2:3], 0, s[30:31]
	v_lshl_add_u64 v[2:3], v[2:3], 0, v[54:55]
	v_lshrrev_b32_e32 v55, 1, v50
	v_and_b32_e32 v56, 32, v232
	v_lshrrev_b32_e32 v56, 1, v56
	v_lshl_add_u64 v[6:7], v[2:3], 0, v[56:57]
	v_add_co_u32_e32 v4, vcc, s6, v6
	s_mov_b32 s6, 0x14610020
	s_nop 0
	v_addc_co_u32_e32 v5, vcc, 0, v7, vcc
	v_lshl_add_u64 v[2:3], v[6:7], 0, s[36:37]
	v_add_co_u32_e32 v6, vcc, s6, v6
	global_load_dwordx4 v[10:13], v[4:5], off
	s_nop 0
	global_load_dwordx4 v[2:5], v[2:3], off offset:64
	v_addc_co_u32_e32 v7, vcc, 0, v7, vcc
	global_load_dwordx4 v[14:17], v[6:7], off
	s_nop 0
	global_load_dwordx4 v[6:9], v[6:7], off offset:64
	v_and_b32_e32 v51, 8, v51
	v_and_b32_e32 v55, 4, v55
	v_and_b32_e32 v57, 0xffffff3, v50
	v_or3_b32 v51, v57, v51, v55
	s_movk_i32 s6, 0x110
	v_mul_lo_u32 v55, v50, s6
	v_mad_u64_u32 v[126:127], s[36:37], v51, s6, v[124:125]
	s_mov_b32 s6, 0x11000
	v_add3_u32 v127, v55, v124, s6
	v_add_u32_e32 v51, 0, v126
	v_add_u32_e32 v55, 0, v127
	s_add_i32 s6, 0, 0x11000
	v_mul_u32_u24_e32 v19, 0x110, v177
	v_add3_u32 v183, s6, v56, v19
	s_lshl_b32 s6, s26, 3
	s_and_b32 s6, s6, 0x700
	s_add_u32 s6, s42, s6
	v_add_u32_e32 v18, 0, v54
	s_addc_u32 s18, s43, 0
	v_add3_u32 v137, v18, v56, v19
	s_add_u32 s26, s6, s47
	v_mov_b64_e32 v[18:19], s[10:11]
	s_addc_u32 s27, s18, s46
	v_mad_i64_i32 v[130:131], s[10:11], v50, s35, v[18:19]
	v_mov_b32_e32 v18, 0
	s_mov_b32 s15, 0
	v_lshl_add_u64 v[128:129], s[26:27], 0, v[52:53]
	v_mov_b32_e32 v19, v18
	v_mov_b32_e32 v20, v18
	v_mov_b32_e32 v21, v18
	v_mov_b32_e32 v22, v18
	v_mov_b32_e32 v23, v18
	v_mov_b32_e32 v24, v18
	v_mov_b32_e32 v25, v18
	v_mov_b32_e32 v26, v18
	v_mov_b32_e32 v27, v18
	v_mov_b32_e32 v28, v18
	v_mov_b32_e32 v29, v18
	v_mov_b32_e32 v30, v18
	v_mov_b32_e32 v31, v18
	v_mov_b32_e32 v32, v18
	v_mov_b32_e32 v33, v18
	v_mov_b32_e32 v38, v18
	v_mov_b32_e32 v39, v18
	v_mov_b32_e32 v40, v18
	v_mov_b32_e32 v41, v18
	v_mov_b32_e32 v46, v18
	v_mov_b32_e32 v47, v18
	v_mov_b32_e32 v48, v18
	v_mov_b32_e32 v49, v18
	v_mov_b32_e32 v62, v18
	v_mov_b32_e32 v63, v18
	v_mov_b32_e32 v64, v18
	v_mov_b32_e32 v65, v18
	v_mov_b32_e32 v74, v18
	v_mov_b32_e32 v75, v18
	v_mov_b32_e32 v76, v18
	v_mov_b32_e32 v77, v18
	v_mov_b32_e32 v34, v18
	v_mov_b32_e32 v35, v18
	v_mov_b32_e32 v36, v18
	v_mov_b32_e32 v37, v18
	v_mov_b32_e32 v42, v18
	v_mov_b32_e32 v43, v18
	v_mov_b32_e32 v44, v18
	v_mov_b32_e32 v45, v18
	v_mov_b32_e32 v50, v18
	v_mov_b32_e32 v51, v18
	v_mov_b32_e32 v52, v18
	v_mov_b32_e32 v53, v18
	v_mov_b32_e32 v54, v18
	v_mov_b32_e32 v55, v18
	v_mov_b32_e32 v56, v18
	v_mov_b32_e32 v57, v18
	v_mov_b32_e32 v58, v18
	v_mov_b32_e32 v59, v18
	v_mov_b32_e32 v60, v18
	v_mov_b32_e32 v61, v18
	v_mov_b32_e32 v66, v18
	v_mov_b32_e32 v67, v18
	v_mov_b32_e32 v68, v18
	v_mov_b32_e32 v69, v18
	v_mov_b32_e32 v70, v18
	v_mov_b32_e32 v71, v18
	v_mov_b32_e32 v72, v18
	v_mov_b32_e32 v73, v18
	v_mov_b32_e32 v78, v18
	v_mov_b32_e32 v79, v18
	v_mov_b32_e32 v80, v18
	v_mov_b32_e32 v81, v18
	v_mov_b32_e32 v122, v18
	v_mov_b32_e32 v123, v18
	s_mov_b32 s11, 0xe054000
	s_mov_b32 s18, 0x16870000
	s_mov_b32 s26, 0xe098000
	s_mov_b32 s27, 0x16880000
	s_mov_b32 s30, 0xe0dc000
	s_mov_b64 s[36:37], 0x40000
	s_waitcnt lgkmcnt(0)
	v_writelane_b32 v175, s64, 0
	v_writelane_b32 v175, s65, 1
	v_writelane_b32 v175, s66, 2
	v_writelane_b32 v175, s67, 3
	v_writelane_b32 v175, s68, 4
	v_writelane_b32 v175, s69, 5
	v_writelane_b32 v175, s70, 6
	v_writelane_b32 v175, s71, 7
	v_writelane_b32 v175, s72, 8
	v_writelane_b32 v175, s73, 9
	v_writelane_b32 v175, s74, 10
	v_writelane_b32 v175, s75, 11
	v_writelane_b32 v175, s76, 12
	v_writelane_b32 v175, s77, 13
	v_writelane_b32 v175, s78, 14
	v_writelane_b32 v175, s79, 15
	v_lshrrev_b32_e32 v200, 4, v232
	v_lshlrev_b32_e32 v201, 11, v200
	v_mul_u32_u24_e32 v202, 0x2200, v200
	v_sub_co_u32_e32 v138, vcc, v128, v201
	s_nop 1
	v_subbrev_co_u32_e32 v139, vcc, 0, v129, vcc
	v_sub_co_u32_e32 v140, vcc, v130, v202
	s_nop 1
	v_subbrev_co_u32_e32 v141, vcc, 0, v131, vcc
	s_nop 1
	v_readfirstlane_b32 s64, v138
	v_readfirstlane_b32 s65, v139
	v_readfirstlane_b32 s72, v140
	v_readfirstlane_b32 s73, v141
	v_and_b32_e32 v203, 15, v200
	v_xor_b32_e32 v203, v203, v177
	v_and_b32_e32 v204, 0x13, v200
	v_lshlrev_b32_e32 v205, 1, v200
	v_and_b32_e32 v205, 8, v205
	v_lshrrev_b32_e32 v206, 1, v200
	v_and_b32_e32 v206, 4, v206
	v_or3_b32 v204, v204, v205, v206
	v_lshlrev_b32_e32 v204, 11, v204
	v_lshl_add_u32 v124, v203, 4, v204
	v_lshl_add_u32 v125, v203, 4, v202
	s_add_u32 s66, s64, s97
	s_addc_u32 s67, s65, 0
	s_sub_u32 s66, s66, 0x40000
	s_subb_u32 s67, s67, 0
	s_add_u32 s68, s64, s18
	s_addc_u32 s69, s65, 0
	s_sub_u32 s68, s68, 0x40000
	s_subb_u32 s69, s69, 0
	s_add_u32 s70, s64, s27
	s_addc_u32 s71, s65, 0
	s_sub_u32 s70, s70, 0x40000
	s_subb_u32 s71, s71, 0
	s_add_u32 s64, s64, s96
	s_addc_u32 s65, s65, 0
	s_sub_u32 s64, s64, 0x40000
	s_subb_u32 s65, s65, 0
	s_add_u32 s74, s72, s11
	s_addc_u32 s75, s73, 0
	s_add_u32 s76, s72, s26
	s_addc_u32 s77, s73, 0
	s_add_u32 s78, s72, s30
	s_addc_u32 s79, s73, 0
	s_add_u32 s72, s72, s91
	s_addc_u32 s73, s73, 0
	v_lshrrev_b32_e32 v205, 6, v232
	s_nop 0
	v_readfirstlane_b32 s11, v205
	s_nop 3
	s_lshl_b32 s11, s11, 10
	s_add_i32 m0, s11, 0x0
	s_nop 0
	global_load_lds_dwordx4 v124, s[64:65]
	s_add_i32 m0, s11, 0x2000
	s_nop 0
	global_load_lds_dwordx4 v124, s[66:67]
	s_add_i32 m0, s11, 0x4000
	s_nop 0
	global_load_lds_dwordx4 v124, s[68:69]
	s_add_i32 m0, s11, 0x6000
	s_nop 0
	global_load_lds_dwordx4 v124, s[70:71]
	s_add_i32 s6, s11, 0x10000
	s_add_i32 m0, s6, 0x0
	s_nop 0
	global_load_lds_dwordx4 v125, s[72:73]
	s_add_i32 m0, s6, 0x2000
	s_nop 0
	global_load_lds_dwordx4 v125, s[74:75]
	s_add_i32 m0, s6, 0x4000
	s_nop 0
	global_load_lds_dwordx4 v125, s[76:77]
	s_add_i32 m0, s6, 0x6000
	s_nop 0
	global_load_lds_dwordx4 v125, s[78:79]
	s_add_u32 s64, s64, 0x40000
	s_addc_u32 s65, s65, 0
	s_add_u32 s72, s72, 0x100
	s_addc_u32 s73, s73, 0
	s_add_u32 s66, s66, 0x40000
	s_addc_u32 s67, s67, 0
	s_add_u32 s74, s74, 0x100
	s_addc_u32 s75, s75, 0
	s_add_u32 s68, s68, 0x40000
	s_addc_u32 s69, s69, 0
	s_add_u32 s76, s76, 0x100
	s_addc_u32 s77, s77, 0
	s_add_u32 s70, s70, 0x40000
	s_addc_u32 s71, s71, 0
	s_add_u32 s78, s78, 0x100
	s_addc_u32 s79, s79, 0
	v_and_b32_e32 v200, 31, v223
	v_lshrrev_b32_e32 v201, 5, v223
	v_and_b32_e32 v202, 15, v200
	v_lshlrev_b32_e32 v200, 8, v200
	v_lshlrev_b32_e32 v203, 3, v179
	v_or3_b32 v204, v203, v201, 0
	v_xor_b32_e32 v204, v204, v202
	v_lshl_add_u32 v82, v204, 4, v200
	v_or3_b32 v204, v203, v201, 2
	v_xor_b32_e32 v204, v204, v202
	v_lshl_add_u32 v83, v204, 4, v200
	v_or3_b32 v204, v203, v201, 4
	v_xor_b32_e32 v204, v204, v202
	v_lshl_add_u32 v84, v204, 4, v200
	v_or3_b32 v204, v203, v201, 6
	v_xor_b32_e32 v204, v204, v202
	v_lshl_add_u32 v85, v204, 4, v200
	v_add_u32_e32 v200, 0x10000, v200
	v_or_b32_e32 v204, 0, v201
	v_xor_b32_e32 v204, v204, v202
	v_lshl_add_u32 v86, v204, 4, v200
	v_or_b32_e32 v204, 2, v201
	v_xor_b32_e32 v204, v204, v202
	v_lshl_add_u32 v87, v204, 4, v200
	v_or_b32_e32 v204, 4, v201
	v_xor_b32_e32 v204, v204, v202
	v_lshl_add_u32 v88, v204, 4, v200
	v_or_b32_e32 v204, 6, v201
	v_xor_b32_e32 v204, v204, v202
	v_lshl_add_u32 v89, v204, 4, v200
	v_or_b32_e32 v204, 8, v201
	v_xor_b32_e32 v204, v204, v202
	v_lshl_add_u32 v90, v204, 4, v200
	v_or_b32_e32 v204, 10, v201
	v_xor_b32_e32 v204, v204, v202
	v_lshl_add_u32 v91, v204, 4, v200
	v_or_b32_e32 v204, 12, v201
	v_xor_b32_e32 v204, v204, v202
	v_lshl_add_u32 v92, v204, 4, v200
	v_or_b32_e32 v204, 14, v201
	v_xor_b32_e32 v204, v204, v202
	v_lshl_add_u32 v93, v204, 4, v200
	s_mov_b32 s15, 0
	s_waitcnt vmcnt(0)
	s_barrier
	.p2align 6
